# attention epilogues (global + windowed): the four silu-gate loads are issued together at loop exit instead of one blocking load per 64-row round
# speedup vs baseline: 1.0316x; 1.0102x over previous
; #define LAS __attribute__((address_space(3)))
; template <bool TRACK> ...
;     ...
;             for (int d = 0; d < 4; ++d) { kf[2 * d] = *(const LAS bf16x8*)(Kbuf + (r32 * 72 + d * 16 + hi * 8) * 2); kf[2 * d + 1] = *(const LAS bf16x8*)(Kbuf + ((32 + r32) * 72 + d * 16 + hi * 8) * 2); }
;             __builtin_amdgcn_sched_barrier(0);
; #pragma unroll
;             for (int d = 0; d < 4; ++d) {
;                 s0 = __builtin_amdgcn_mfma_f32_32x32x16_bf16(kf[2 * d], qf[d], s0, 0, 0, 0);
;                 s1 = __builtin_amdgcn_mfma_f32_32x32x16_bf16(kf[2 * d + 1], qf[d], s1, 0, 0, 0);
;             }
; #pragma unroll
;             for (int kc = 0; kc < 2; ++kc) {
;                 const LAS unsigned char* vp0 = Vbuf + (r32 * 68 + kc * 16 + 4 * hi) * 2; const LAS unsigned char* vp1 = vp0 + 32 * 68 * 2;
;                 vq[4 * kc] = *(const LAS u32x2*)vp0; vq[4 * kc + 1] = *(const LAS u32x2*)(vp0 + 16); vq[4 * kc + 2] = *(const LAS u32x2*)vp1; vq[4 * kc + 3] = *(const LAS u32x2*)(vp1 + 16); }
;             __builtin_amdgcn_sched_barrier(0);
;             } else {
; #pragma unroll
;             for (int d = 0; d < 4; ++d) {
;                 const bf16x8 a0 = *(const LAS bf16x8*)(Kbuf + (r32 * 72 + d * 16 + hi * 8) * 2);
;                 const bf16x8 a1 = *(const LAS bf16x8*)(Kbuf + ((32 + r32) * 72 + d * 16 + hi * 8) * 2);
;                 s0 = __builtin_amdgcn_mfma_f32_32x32x16_bf16(a0, qf[d], s0, 0, 0, 0);
;                 s1 = __builtin_amdgcn_mfma_f32_32x32x16_bf16(a1, qf[d], s1, 0, 0, 0);
;             }
;             }
;             if (mt) { const int qpos = qstart + wave * 32 + r32;
; #pragma unroll
;                 for (int r = 0; r < 16; ++r) { const int d0 = qpos - (kpos0 + crow(r, hi)); if (d0 > 128 || d0 < -128) s0[r] = -INFINITY; const int d1 = d0 - 32; if (d1 > 128 || d1 < -128) s1[r] = -INFINITY; } }
;             if (TRACK) {
;             float mx = fmaxf(fmaxf(s0[0], s1[0]), s0[1]);
; #pragma unroll
;             for (int r = 1; r < 15; r += 2) mx = fmaxf(fmaxf(mx, s1[r]), fmaxf(fmaxf(s0[r + 1], s1[r + 1]), s0[r + 2 < 16 ? r + 2 : 15]));
;             mx = fmaxf(mx, s1[15]);
;             mx = fmaxf(mx, __shfl_xor(mx, 32));
;             if (__any(mx > ATT_THR)) {
;                 const float dl = fmaxf(mx, 0.f); m += dl; const float alpha = __builtin_amdgcn_exp2f(-dl); lsum *= alpha;
; #pragma unroll
.LBB0_167:
	global_load_dwordx4 v[98:101], v[114:115], off
	global_load_dwordx4 v[102:105], v[116:117], off
	ds_read_b128 v[106:109], v204 offset:18432
	ds_read_b128 v[110:113], v202 offset:18432
	ds_read_b128 v[158:161], v204 offset:18464
	ds_read2_b64 v[206:209], v247 offset0:128 offset1:130
	ds_read2_b64 v[210:213], v0 offset0:160 offset1:162
	v_lshl_add_u64 v[114:115], v[114:115], 0, s[4:5]
	v_lshl_add_u64 v[116:117], v[116:117], 0, s[38:39]
	s_waitcnt lgkmcnt(4)
	v_mfma_f32_32x32x16_bf16 v[214:229], v[106:109], v[94:97], 0
	ds_read_b128 v[106:109], v202 offset:18464
	v_exp_f32_e32 v58, v58
	v_exp_f32_e32 v59, v59
	v_exp_f32_e32 v60, v60
	s_waitcnt lgkmcnt(4)
	v_mfma_f32_32x32x16_bf16 v[230:245], v[110:113], v[94:97], 0
	ds_read_b128 v[110:113], v204 offset:18496
	v_exp_f32_e32 v61, v61
	v_exp_f32_e32 v62, v62
	v_exp_f32_e32 v63, v63
	s_waitcnt lgkmcnt(4)
	v_mfma_f32_32x32x16_bf16 v[214:229], v[158:161], v[90:93], v[214:229]
	ds_read_b128 v[158:161], v202 offset:18496
	v_exp_f32_e32 v64, v64
	v_exp_f32_e32 v65, v65
	v_cvt_pk_bf16_f32 v54, v58, v59
	s_waitcnt lgkmcnt(2)
	v_mfma_f32_32x32x16_bf16 v[230:245], v[106:109], v[90:93], v[230:245]
	ds_read_b128 v[106:109], v204 offset:18528
	v_cvt_pk_bf16_f32 v55, v60, v61
	v_cvt_pk_bf16_f32 v56, v62, v63
	v_cvt_pk_bf16_f32 v57, v64, v65
	s_waitcnt lgkmcnt(2)
	v_mfma_f32_32x32x16_bf16 v[214:229], v[110:113], v[86:89], v[214:229]
	ds_read_b128 v[110:113], v202 offset:18528
	v_exp_f32_e32 v66, v66
	v_exp_f32_e32 v67, v67
	v_exp_f32_e32 v68, v68
	s_waitcnt lgkmcnt(2)
	v_mfma_f32_32x32x16_bf16 v[230:245], v[158:161], v[86:89], v[230:245]
	v_exp_f32_e32 v69, v69
	v_exp_f32_e32 v70, v70
	v_exp_f32_e32 v71, v71
	s_waitcnt lgkmcnt(1)
	v_mfma_f32_32x32x16_bf16 v[214:229], v[106:109], v[82:85], v[214:229]
	v_exp_f32_e32 v72, v72
	v_exp_f32_e32 v73, v73
	v_cvt_pk_bf16_f32 v66, v66, v67
	s_waitcnt lgkmcnt(0)
	v_mfma_f32_32x32x16_bf16 v[230:245], v[110:113], v[82:85], v[230:245]
	v_cvt_pk_bf16_f32 v67, v68, v69
	v_cvt_pk_bf16_f32 v68, v70, v71
	v_cvt_pk_bf16_f32 v69, v72, v73
	v_mfma_f32_32x32x16_bf16 v[2:17], v[206:209], v[50:53], v[2:17]
	ds_read2_b64 v[206:209], v247 offset0:132 offset1:134
	v_exp_f32_e32 v74, v74
	v_exp_f32_e32 v75, v75
	v_exp_f32_e32 v76, v76
	v_mfma_f32_32x32x16_bf16 v[18:33], v[210:213], v[50:53], v[18:33]
	ds_read2_b64 v[210:213], v0 offset0:164 offset1:166
	v_exp_f32_e32 v77, v77
	v_exp_f32_e32 v78, v78
	v_exp_f32_e32 v79, v79
	v_mfma_f32_4x4x4_16b_bf16 v[34:37], v[118:119], v[50:51], v[34:37]
	v_mfma_f32_4x4x4_16b_bf16 v[38:41], v[118:119], v[52:53], v[38:41]
	v_exp_f32_e32 v80, v80
	v_exp_f32_e32 v81, v81
	s_waitcnt lgkmcnt(1)
	v_mfma_f32_32x32x16_bf16 v[2:17], v[206:209], v[54:57], v[2:17]
	ds_read2_b64 v[206:209], v247 offset0:136 offset1:138
	v_cvt_pk_bf16_f32 v70, v74, v75
	v_cvt_pk_bf16_f32 v71, v76, v77
	v_cvt_pk_bf16_f32 v72, v78, v79
	s_waitcnt lgkmcnt(1)
	v_mfma_f32_32x32x16_bf16 v[18:33], v[210:213], v[54:57], v[18:33]
	ds_read2_b64 v[210:213], v0 offset0:168 offset1:170
	v_cvt_pk_bf16_f32 v73, v80, v81
	v_mfma_f32_4x4x4_16b_bf16 v[34:37], v[118:119], v[54:55], v[34:37]
	v_mfma_f32_4x4x4_16b_bf16 v[38:41], v[118:119], v[56:57], v[38:41]
	s_waitcnt vmcnt(1)
	ds_write_b128 v201, v[98:101] offset:0
	s_waitcnt vmcnt(0)
	ds_write2_b64 v127, v[102:103], v[104:105] offset1:1
	s_waitcnt lgkmcnt(3)
	v_mfma_f32_32x32x16_bf16 v[2:17], v[206:209], v[66:69], v[2:17]
	ds_read2_b64 v[206:209], v247 offset0:140 offset1:142
	v_exp_f32_e32 v214, v214
	v_exp_f32_e32 v215, v215
	v_exp_f32_e32 v216, v216
	s_waitcnt lgkmcnt(3)
	v_mfma_f32_32x32x16_bf16 v[18:33], v[210:213], v[66:69], v[18:33]
	ds_read2_b64 v[210:213], v0 offset0:172 offset1:174
	v_exp_f32_e32 v217, v217
	v_exp_f32_e32 v218, v218
	v_mfma_f32_4x4x4_16b_bf16 v[34:37], v[118:119], v[66:67], v[34:37]
	v_mfma_f32_4x4x4_16b_bf16 v[38:41], v[118:119], v[68:69], v[38:41]
	s_waitcnt lgkmcnt(1)
	v_mfma_f32_32x32x16_bf16 v[2:17], v[206:209], v[70:73], v[2:17]
	v_exp_f32_e32 v219, v219
	v_exp_f32_e32 v220, v220
	v_exp_f32_e32 v221, v221
	s_waitcnt lgkmcnt(0)
	v_mfma_f32_32x32x16_bf16 v[18:33], v[210:213], v[70:73], v[18:33]
	v_cvt_pk_bf16_f32 v214, v214, v215
	v_cvt_pk_bf16_f32 v215, v216, v217
	v_cvt_pk_bf16_f32 v216, v218, v219
	v_mfma_f32_4x4x4_16b_bf16 v[34:37], v[118:119], v[70:71], v[34:37]
	v_mfma_f32_4x4x4_16b_bf16 v[38:41], v[118:119], v[72:73], v[38:41]
	v_cvt_pk_bf16_f32 v217, v220, v221
	s_waitcnt lgkmcnt(0)
	s_barrier
; #define LAS __attribute__((address_space(3)))
; template <bool TRACK> ...
;     ...
;             for (int d = 0; d < 4; ++d) { kf[2 * d] = *(const LAS bf16x8*)(Kbuf + (r32 * 72 + d * 16 + hi * 8) * 2); kf[2 * d + 1] = *(const LAS bf16x8*)(Kbuf + ((32 + r32) * 72 + d * 16 + hi * 8) * 2); }
;             __builtin_amdgcn_sched_barrier(0);
; #pragma unroll
;             for (int d = 0; d < 4; ++d) {
;                 s0 = __builtin_amdgcn_mfma_f32_32x32x16_bf16(kf[2 * d], qf[d], s0, 0, 0, 0);
;                 s1 = __builtin_amdgcn_mfma_f32_32x32x16_bf16(kf[2 * d + 1], qf[d], s1, 0, 0, 0);
;             }
; #pragma unroll
;             for (int kc = 0; kc < 2; ++kc) {
;                 const LAS unsigned char* vp0 = Vbuf + (r32 * 68 + kc * 16 + 4 * hi) * 2; const LAS unsigned char* vp1 = vp0 + 32 * 68 * 2;
;                 vq[4 * kc] = *(const LAS u32x2*)vp0; vq[4 * kc + 1] = *(const LAS u32x2*)(vp0 + 16); vq[4 * kc + 2] = *(const LAS u32x2*)vp1; vq[4 * kc + 3] = *(const LAS u32x2*)(vp1 + 16); }
;             __builtin_amdgcn_sched_barrier(0);
;             } else {
; #pragma unroll
;             for (int d = 0; d < 4; ++d) {
;                 const bf16x8 a0 = *(const LAS bf16x8*)(Kbuf + (r32 * 72 + d * 16 + hi * 8) * 2);
;                 const bf16x8 a1 = *(const LAS bf16x8*)(Kbuf + ((32 + r32) * 72 + d * 16 + hi * 8) * 2);
;                 s0 = __builtin_amdgcn_mfma_f32_32x32x16_bf16(a0, qf[d], s0, 0, 0, 0);
;                 s1 = __builtin_amdgcn_mfma_f32_32x32x16_bf16(a1, qf[d], s1, 0, 0, 0);
;             }
;             }
;             if (mt) { const int qpos = qstart + wave * 32 + r32;
; #pragma unroll
;                 for (int r = 0; r < 16; ++r) { const int d0 = qpos - (kpos0 + crow(r, hi)); if (d0 > 128 || d0 < -128) s0[r] = -INFINITY; const int d1 = d0 - 32; if (d1 > 128 || d1 < -128) s1[r] = -INFINITY; } }
;             if (TRACK) {
;             float mx = fmaxf(fmaxf(s0[0], s1[0]), s0[1]);
; #pragma unroll
;             for (int r = 1; r < 15; r += 2) mx = fmaxf(fmaxf(mx, s1[r]), fmaxf(fmaxf(s0[r + 1], s1[r + 1]), s0[r + 2 < 16 ? r + 2 : 15]));
;             mx = fmaxf(mx, s1[15]);
;             mx = fmaxf(mx, __shfl_xor(mx, 32));
;             if (__any(mx > ATT_THR)) {
;                 const float dl = fmaxf(mx, 0.f); m += dl; const float alpha = __builtin_amdgcn_exp2f(-dl); lsum *= alpha;
; #pragma unroll
	global_load_dwordx4 v[98:101], v[114:115], off
	global_load_dwordx4 v[102:105], v[116:117], off
	ds_read_b128 v[106:109], v204 offset:0
	ds_read_b128 v[110:113], v202 offset:0
	ds_read_b128 v[158:161], v204 offset:32
	ds_read2_b64 v[206:209], v123 offset0:128 offset1:130
	ds_read2_b64 v[210:213], v125 offset0:160 offset1:162
	v_lshl_add_u64 v[114:115], v[114:115], 0, s[4:5]
	v_lshl_add_u64 v[116:117], v[116:117], 0, s[38:39]
	s_waitcnt lgkmcnt(4)
	v_mfma_f32_32x32x16_bf16 v[50:65], v[106:109], v[94:97], 0
	ds_read_b128 v[106:109], v202 offset:32
	v_exp_f32_e32 v222, v222
	v_exp_f32_e32 v223, v223
	v_exp_f32_e32 v224, v224
	s_waitcnt lgkmcnt(4)
	v_mfma_f32_32x32x16_bf16 v[66:81], v[110:113], v[94:97], 0
	ds_read_b128 v[110:113], v204 offset:64
	v_exp_f32_e32 v225, v225
	v_exp_f32_e32 v226, v226
	v_exp_f32_e32 v227, v227
	s_waitcnt lgkmcnt(4)
	v_mfma_f32_32x32x16_bf16 v[50:65], v[158:161], v[90:93], v[50:65]
	ds_read_b128 v[158:161], v202 offset:64
	v_exp_f32_e32 v228, v228
	v_exp_f32_e32 v229, v229
	v_cvt_pk_bf16_f32 v218, v222, v223
	s_waitcnt lgkmcnt(2)
	v_mfma_f32_32x32x16_bf16 v[66:81], v[106:109], v[90:93], v[66:81]
	ds_read_b128 v[106:109], v204 offset:96
	v_cvt_pk_bf16_f32 v219, v224, v225
	v_cvt_pk_bf16_f32 v220, v226, v227
	v_cvt_pk_bf16_f32 v221, v228, v229
	s_waitcnt lgkmcnt(2)
	v_mfma_f32_32x32x16_bf16 v[50:65], v[110:113], v[86:89], v[50:65]
	ds_read_b128 v[110:113], v202 offset:96
	v_exp_f32_e32 v230, v230
	v_exp_f32_e32 v231, v231
	v_exp_f32_e32 v232, v232
	s_waitcnt lgkmcnt(2)
	v_mfma_f32_32x32x16_bf16 v[66:81], v[158:161], v[86:89], v[66:81]
	v_exp_f32_e32 v233, v233
	v_exp_f32_e32 v234, v234
	v_exp_f32_e32 v235, v235
	s_waitcnt lgkmcnt(1)
	v_mfma_f32_32x32x16_bf16 v[50:65], v[106:109], v[82:85], v[50:65]
	v_exp_f32_e32 v236, v236
	v_exp_f32_e32 v237, v237
	v_cvt_pk_bf16_f32 v230, v230, v231
	s_waitcnt lgkmcnt(0)
	v_mfma_f32_32x32x16_bf16 v[66:81], v[110:113], v[82:85], v[66:81]
	v_cvt_pk_bf16_f32 v231, v232, v233
	v_cvt_pk_bf16_f32 v232, v234, v235
	v_cvt_pk_bf16_f32 v233, v236, v237
	v_mfma_f32_32x32x16_bf16 v[2:17], v[206:209], v[214:217], v[2:17]
	ds_read2_b64 v[206:209], v123 offset0:132 offset1:134
	v_exp_f32_e32 v238, v238
	v_exp_f32_e32 v239, v239
	v_exp_f32_e32 v240, v240
	v_mfma_f32_32x32x16_bf16 v[18:33], v[210:213], v[214:217], v[18:33]
	ds_read2_b64 v[210:213], v125 offset0:164 offset1:166
	v_exp_f32_e32 v241, v241
	v_exp_f32_e32 v242, v242
	v_exp_f32_e32 v243, v243
	v_mfma_f32_4x4x4_16b_bf16 v[34:37], v[118:119], v[214:215], v[34:37]
	v_mfma_f32_4x4x4_16b_bf16 v[38:41], v[118:119], v[216:217], v[38:41]
	v_exp_f32_e32 v244, v244
	v_exp_f32_e32 v245, v245
	s_waitcnt lgkmcnt(1)
	v_mfma_f32_32x32x16_bf16 v[2:17], v[206:209], v[218:221], v[2:17]
	ds_read2_b64 v[206:209], v123 offset0:136 offset1:138
	v_cvt_pk_bf16_f32 v234, v238, v239
	v_cvt_pk_bf16_f32 v235, v240, v241
	v_cvt_pk_bf16_f32 v236, v242, v243
	s_waitcnt lgkmcnt(1)
	v_mfma_f32_32x32x16_bf16 v[18:33], v[210:213], v[218:221], v[18:33]
	ds_read2_b64 v[210:213], v125 offset0:168 offset1:170
	v_cvt_pk_bf16_f32 v237, v244, v245
	v_mfma_f32_4x4x4_16b_bf16 v[34:37], v[118:119], v[218:219], v[34:37]
	v_mfma_f32_4x4x4_16b_bf16 v[38:41], v[118:119], v[220:221], v[38:41]
	s_waitcnt vmcnt(1)
	ds_write_b128 v201, v[98:101] offset:18432
	s_waitcnt vmcnt(0)
	ds_write2_b64 v129, v[102:103], v[104:105] offset1:1
	s_waitcnt lgkmcnt(3)
	v_mfma_f32_32x32x16_bf16 v[2:17], v[206:209], v[230:233], v[2:17]
	ds_read2_b64 v[206:209], v123 offset0:140 offset1:142
	v_exp_f32_e32 v50, v50
	v_exp_f32_e32 v51, v51
	v_exp_f32_e32 v52, v52
	s_waitcnt lgkmcnt(3)
	v_mfma_f32_32x32x16_bf16 v[18:33], v[210:213], v[230:233], v[18:33]
	ds_read2_b64 v[210:213], v125 offset0:172 offset1:174
	v_exp_f32_e32 v53, v53
	v_exp_f32_e32 v54, v54
	v_mfma_f32_4x4x4_16b_bf16 v[34:37], v[118:119], v[230:231], v[34:37]
	v_mfma_f32_4x4x4_16b_bf16 v[38:41], v[118:119], v[232:233], v[38:41]
	s_waitcnt lgkmcnt(1)
	v_mfma_f32_32x32x16_bf16 v[2:17], v[206:209], v[234:237], v[2:17]
	v_exp_f32_e32 v55, v55
	v_exp_f32_e32 v56, v56
	v_exp_f32_e32 v57, v57
	s_waitcnt lgkmcnt(0)
	v_mfma_f32_32x32x16_bf16 v[18:33], v[210:213], v[234:237], v[18:33]
	v_cvt_pk_bf16_f32 v50, v50, v51
	v_cvt_pk_bf16_f32 v51, v52, v53
	v_cvt_pk_bf16_f32 v52, v54, v55
	v_mfma_f32_4x4x4_16b_bf16 v[34:37], v[118:119], v[234:235], v[34:37]
	v_mfma_f32_4x4x4_16b_bf16 v[38:41], v[118:119], v[236:237], v[38:41]
	v_cvt_pk_bf16_f32 v53, v56, v57
	s_add_i32 s20, s20, 2
	s_cmp_lg_u32 s20, 36
	s_waitcnt lgkmcnt(0)
	s_barrier
	s_cbranch_scc1 .LBB0_167
	global_load_dwordx4 v[214:217], v[154:155], off offset:1280
	global_load_dwordx4 v[218:221], v[150:151], off offset:1280
	global_load_dwordx4 v[222:225], v[142:143], off offset:1280
	global_load_dwordx4 v[226:229], v[138:139], off offset:1280
	s_nop 15
	v_readlane_b32 s89, v248, 3
	v_add_f32_e32 v34, v34, v38
	s_nop 0
	ds_bpermute_b32 v35, v188, v34
	s_waitcnt lgkmcnt(0)
	v_add_f32_e32 v34, v34, v35
	s_nop 0
	v_div_scale_f32 v0, s[20:21], v34, v34, 1.0
	v_rcp_f32_e32 v35, v0
	s_waitcnt lgkmcnt(0)
	s_barrier
; #define LAS __attribute__((address_space(3)))
; __device__ __forceinline__ unsigned pk2(float lo, float hi) { f32x2_t v = {lo, hi}; bf16x2_t b = __builtin_convertvector(v, bf16x2_t); return __builtin_bit_cast(unsigned, b); }
; __device__ __forceinline__ float silu_f(float v) { return v * __builtin_amdgcn_rcpf(1.0f + __expf(-v)); }
; template <bool TRACK> ...
;     ...
;         const int pc = lane & 7;
; #pragma unroll
;         for (int i = 0; i < 4; ++i) { const int rw = i * 8 + (lane >> 3), row = wave * 32 + rw;
;             const f32x4 oa = *(const LAS f32x4*)(scr + rw * 272 + pc * 32), ob = *(const LAS f32x4*)(scr + rw * 272 + pc * 32 + 16);
;             float gv[8]; unpack8(*(const u32x4*)(gate + (size_t)row * INW + 8 * pc), gv);
;             u32x4 w; w.x = pk2(oa.x * silu_f(gv[0]), oa.y * silu_f(gv[1])); w.y = pk2(oa.z * silu_f(gv[2]), oa.w * silu_f(gv[3]));
;             w.z = pk2(ob.x * silu_f(gv[4]), ob.y * silu_f(gv[5])); w.w = pk2(ob.z * silu_f(gv[6]), ob.w * silu_f(gv[7]));
;             *(u32x4*)(outp + (size_t)row * DM + 8 * pc) = w; }
	v_fma_f32 v36, -v0, v35, 1.0
	v_fmac_f32_e32 v35, v36, v35
	v_div_scale_f32 v36, vcc, 1.0, v34, 1.0
	v_mul_f32_e32 v37, v36, v35
	v_fma_f32 v38, -v0, v37, v36
	v_fmac_f32_e32 v37, v38, v35
	v_fma_f32 v0, -v0, v37, v36
	v_div_fmas_f32 v0, v0, v35, v37
	v_div_fixup_f32 v0, v0, v34, 1.0
	s_nop 1
	v_mul_f32_e64 v2, v2, v0
	v_mul_f32_e64 v3, v3, v0
	v_pk_mul_f32 v[4:5], v[4:5], v[0:1] op_sel_hi:[1,0]
	v_add_u32_e32 v34, v198, v156
	ds_write_b128 v34, v[2:5] offset:40960
	v_pk_mul_f32 v[2:3], v[6:7], v[0:1] op_sel_hi:[1,0]
	v_pk_mul_f32 v[4:5], v[8:9], v[0:1] op_sel_hi:[1,0]
	ds_write_b128 v34, v[2:5] offset:40992
	v_pk_mul_f32 v[2:3], v[10:11], v[0:1] op_sel_hi:[1,0]
	v_pk_mul_f32 v[4:5], v[12:13], v[0:1] op_sel_hi:[1,0]
	ds_write_b128 v34, v[2:5] offset:41024
	v_pk_mul_f32 v[2:3], v[14:15], v[0:1] op_sel_hi:[1,0]
	v_pk_mul_f32 v[4:5], v[16:17], v[0:1] op_sel_hi:[1,0]
	ds_write_b128 v34, v[2:5] offset:41056
	v_pk_mul_f32 v[2:3], v[18:19], v[0:1] op_sel_hi:[1,0]
	v_pk_mul_f32 v[4:5], v[20:21], v[0:1] op_sel_hi:[1,0]
	ds_write_b128 v34, v[2:5] offset:41088
	v_pk_mul_f32 v[2:3], v[22:23], v[0:1] op_sel_hi:[1,0]
	v_pk_mul_f32 v[4:5], v[24:25], v[0:1] op_sel_hi:[1,0]
	ds_write_b128 v34, v[2:5] offset:41120
	v_pk_mul_f32 v[2:3], v[26:27], v[0:1] op_sel_hi:[1,0]
	v_pk_mul_f32 v[4:5], v[28:29], v[0:1] op_sel_hi:[1,0]
	ds_write_b128 v34, v[2:5] offset:41152
	v_pk_mul_f32 v[2:3], v[30:31], v[0:1] op_sel_hi:[1,0]
	v_pk_mul_f32 v[4:5], v[32:33], v[0:1] op_sel_hi:[1,0]
	ds_write_b128 v34, v[2:5] offset:41184
	v_add_u32_e32 v0, v192, v193
	ds_read_b128 v[6:9], v0 offset:40960
	ds_read_b128 v[2:5], v0 offset:40976
	s_waitcnt vmcnt(3)
	v_lshlrev_b32_e32 v14, 16, v214
	v_and_b32_e32 v15, 0xffff0000, v214
	v_mul_f32_e32 v214, 0xbfb8aa3b, v14
	v_exp_f32_e32 v214, v214
	s_nop 0
	v_add_f32_e32 v214, 1.0, v214
	v_rcp_f32_e32 v16, v214
	v_mul_f32_e32 v214, 0xbfb8aa3b, v15
	v_exp_f32_e32 v214, v214
	s_nop 0
	v_add_f32_e32 v214, 1.0, v214
	v_rcp_f32_e32 v17, v214
	v_lshlrev_b32_e32 v214, 16, v215
	v_and_b32_e32 v215, 0xffff0000, v215
	v_pk_mul_f32 v[14:15], v[16:17], v[14:15]
	s_waitcnt lgkmcnt(1)
	v_pk_mul_f32 v[6:7], v[6:7], v[14:15]
	s_nop 0
	v_cvt_pk_bf16_f32 v6, v6, v7
	v_mul_f32_e32 v7, 0xbfb8aa3b, v214
	v_exp_f32_e32 v7, v7
	s_nop 0
	v_add_f32_e32 v7, 1.0, v7
	v_rcp_f32_e32 v14, v7
	v_mul_f32_e32 v7, 0xbfb8aa3b, v215
	v_exp_f32_e32 v7, v7
	s_nop 0
	v_add_f32_e32 v7, 1.0, v7
	v_rcp_f32_e32 v15, v7
	s_nop 0
	v_pk_mul_f32 v[214:215], v[14:15], v[214:215]
	s_nop 0
	v_pk_mul_f32 v[8:9], v[8:9], v[214:215]
	s_nop 0
	v_cvt_pk_bf16_f32 v7, v8, v9
	v_lshlrev_b32_e32 v8, 16, v216
	v_and_b32_e32 v9, 0xffff0000, v216
	v_mul_f32_e32 v214, 0xbfb8aa3b, v8
	v_mul_f32_e32 v215, 0xbfb8aa3b, v9
	v_exp_f32_e32 v214, v214
	v_exp_f32_e32 v215, v215
	v_add_f32_e32 v214, 1.0, v214
	v_add_f32_e32 v215, 1.0, v215
	v_rcp_f32_e32 v214, v214
	v_rcp_f32_e32 v215, v215
	s_nop 0
	v_pk_mul_f32 v[8:9], v[214:215], v[8:9]
	s_waitcnt lgkmcnt(0)
	v_pk_mul_f32 v[2:3], v[2:3], v[8:9]
	s_nop 0
	v_cvt_pk_bf16_f32 v8, v2, v3
	v_lshlrev_b32_e32 v2, 16, v217
	v_mul_f32_e32 v9, 0xbfb8aa3b, v2
	v_exp_f32_e32 v9, v9
	v_and_b32_e32 v3, 0xffff0000, v217
	v_add_f32_e32 v9, 1.0, v9
	v_rcp_f32_e32 v214, v9
	v_mul_f32_e32 v9, 0xbfb8aa3b, v3
	v_exp_f32_e32 v9, v9
	s_nop 0
	v_add_f32_e32 v9, 1.0, v9
	v_rcp_f32_e32 v215, v9
	s_nop 0
	v_pk_mul_f32 v[2:3], v[214:215], v[2:3]
	s_nop 0
	v_pk_mul_f32 v[2:3], v[4:5], v[2:3]
	s_nop 0
	v_cvt_pk_bf16_f32 v9, v2, v3
	global_store_dwordx4 v[152:153], v[6:9], off
	ds_read_b128 v[6:9], v0 offset:43136
	ds_read_b128 v[2:5], v0 offset:43152
	s_waitcnt vmcnt(3)
	v_lshlrev_b32_e32 v14, 16, v218
	v_and_b32_e32 v15, 0xffff0000, v218
	v_mul_f32_e32 v218, 0xbfb8aa3b, v14
	v_exp_f32_e32 v218, v218
	s_nop 0
	v_add_f32_e32 v218, 1.0, v218
	v_rcp_f32_e32 v16, v218
	v_mul_f32_e32 v218, 0xbfb8aa3b, v15
	v_exp_f32_e32 v218, v218
	s_nop 0
	v_add_f32_e32 v218, 1.0, v218
	v_rcp_f32_e32 v17, v218
	v_lshlrev_b32_e32 v218, 16, v219
	v_and_b32_e32 v219, 0xffff0000, v219
	v_pk_mul_f32 v[14:15], v[16:17], v[14:15]
	s_waitcnt lgkmcnt(1)
	v_pk_mul_f32 v[6:7], v[6:7], v[14:15]
	s_nop 0
	v_cvt_pk_bf16_f32 v6, v6, v7
	v_mul_f32_e32 v7, 0xbfb8aa3b, v218
	v_exp_f32_e32 v7, v7
	s_nop 0
	v_add_f32_e32 v7, 1.0, v7
	v_rcp_f32_e32 v14, v7
	v_mul_f32_e32 v7, 0xbfb8aa3b, v219
	v_exp_f32_e32 v7, v7
	s_nop 0
	v_add_f32_e32 v7, 1.0, v7
	v_rcp_f32_e32 v15, v7
	s_nop 0
	v_pk_mul_f32 v[218:219], v[14:15], v[218:219]
	s_nop 0
	v_pk_mul_f32 v[8:9], v[8:9], v[218:219]
	s_nop 0
	v_cvt_pk_bf16_f32 v7, v8, v9
	v_lshlrev_b32_e32 v8, 16, v220
	v_and_b32_e32 v9, 0xffff0000, v220
	v_mul_f32_e32 v218, 0xbfb8aa3b, v8
	v_mul_f32_e32 v219, 0xbfb8aa3b, v9
	v_exp_f32_e32 v218, v218
	v_exp_f32_e32 v219, v219
	v_add_f32_e32 v218, 1.0, v218
	v_add_f32_e32 v219, 1.0, v219
	v_rcp_f32_e32 v218, v218
	v_rcp_f32_e32 v219, v219
	s_nop 0
	v_pk_mul_f32 v[8:9], v[218:219], v[8:9]
	s_waitcnt lgkmcnt(0)
; #define LAS __attribute__((address_space(3)))
; __device__ __forceinline__ unsigned pk2(float lo, float hi) { f32x2_t v = {lo, hi}; bf16x2_t b = __builtin_convertvector(v, bf16x2_t); return __builtin_bit_cast(unsigned, b); }
; __device__ __forceinline__ float silu_f(float v) { return v * __builtin_amdgcn_rcpf(1.0f + __expf(-v)); }
; template <bool TRACK> ...
;     ...
;         const int pc = lane & 7;
; #pragma unroll
;         for (int i = 0; i < 4; ++i) { const int rw = i * 8 + (lane >> 3), row = wave * 32 + rw;
;             const f32x4 oa = *(const LAS f32x4*)(scr + rw * 272 + pc * 32), ob = *(const LAS f32x4*)(scr + rw * 272 + pc * 32 + 16);
;             float gv[8]; unpack8(*(const u32x4*)(gate + (size_t)row * INW + 8 * pc), gv);
;             u32x4 w; w.x = pk2(oa.x * silu_f(gv[0]), oa.y * silu_f(gv[1])); w.y = pk2(oa.z * silu_f(gv[2]), oa.w * silu_f(gv[3]));
;             w.z = pk2(ob.x * silu_f(gv[4]), ob.y * silu_f(gv[5])); w.w = pk2(ob.z * silu_f(gv[6]), ob.w * silu_f(gv[7]));
;             *(u32x4*)(outp + (size_t)row * DM + 8 * pc) = w; }
	v_pk_mul_f32 v[2:3], v[2:3], v[8:9]
	s_nop 0
	v_cvt_pk_bf16_f32 v8, v2, v3
	v_lshlrev_b32_e32 v2, 16, v221
	v_mul_f32_e32 v9, 0xbfb8aa3b, v2
	v_exp_f32_e32 v9, v9
	v_and_b32_e32 v3, 0xffff0000, v221
	v_add_f32_e32 v9, 1.0, v9
	v_rcp_f32_e32 v218, v9
	v_mul_f32_e32 v9, 0xbfb8aa3b, v3
	v_exp_f32_e32 v9, v9
	s_nop 0
	v_add_f32_e32 v9, 1.0, v9
	v_rcp_f32_e32 v219, v9
	s_nop 0
	v_pk_mul_f32 v[2:3], v[218:219], v[2:3]
	s_nop 0
	v_pk_mul_f32 v[2:3], v[4:5], v[2:3]
	s_nop 0
	v_cvt_pk_bf16_f32 v9, v2, v3
	global_store_dwordx4 v[144:145], v[6:9], off
	ds_read_b128 v[6:9], v0 offset:45312
	ds_read_b128 v[2:5], v0 offset:45328
	s_waitcnt vmcnt(3)
	v_lshlrev_b32_e32 v14, 16, v222
	v_and_b32_e32 v15, 0xffff0000, v222
	v_mul_f32_e32 v222, 0xbfb8aa3b, v14
	v_exp_f32_e32 v222, v222
	s_nop 0
	v_add_f32_e32 v222, 1.0, v222
	v_rcp_f32_e32 v16, v222
	v_mul_f32_e32 v222, 0xbfb8aa3b, v15
	v_exp_f32_e32 v222, v222
	s_nop 0
	v_add_f32_e32 v222, 1.0, v222
	v_rcp_f32_e32 v17, v222
	v_lshlrev_b32_e32 v222, 16, v223
	v_and_b32_e32 v223, 0xffff0000, v223
	v_pk_mul_f32 v[14:15], v[16:17], v[14:15]
	s_waitcnt lgkmcnt(1)
	v_pk_mul_f32 v[6:7], v[6:7], v[14:15]
	s_nop 0
	v_cvt_pk_bf16_f32 v6, v6, v7
	v_mul_f32_e32 v7, 0xbfb8aa3b, v222
	v_exp_f32_e32 v7, v7
	s_nop 0
	v_add_f32_e32 v7, 1.0, v7
	v_rcp_f32_e32 v14, v7
	v_mul_f32_e32 v7, 0xbfb8aa3b, v223
	v_exp_f32_e32 v7, v7
	s_nop 0
	v_add_f32_e32 v7, 1.0, v7
	v_rcp_f32_e32 v15, v7
	s_nop 0
	v_pk_mul_f32 v[222:223], v[14:15], v[222:223]
	s_nop 0
	v_pk_mul_f32 v[8:9], v[8:9], v[222:223]
	s_nop 0
	v_cvt_pk_bf16_f32 v7, v8, v9
	v_lshlrev_b32_e32 v8, 16, v224
	v_and_b32_e32 v9, 0xffff0000, v224
	v_mul_f32_e32 v222, 0xbfb8aa3b, v8
	v_mul_f32_e32 v223, 0xbfb8aa3b, v9
	v_exp_f32_e32 v222, v222
	v_exp_f32_e32 v223, v223
	v_add_f32_e32 v222, 1.0, v222
	v_add_f32_e32 v223, 1.0, v223
	v_rcp_f32_e32 v222, v222
	v_rcp_f32_e32 v223, v223
	s_nop 0
	v_pk_mul_f32 v[8:9], v[222:223], v[8:9]
	s_waitcnt lgkmcnt(0)
	v_pk_mul_f32 v[2:3], v[2:3], v[8:9]
	s_nop 0
	v_cvt_pk_bf16_f32 v8, v2, v3
	v_lshlrev_b32_e32 v2, 16, v225
	v_mul_f32_e32 v9, 0xbfb8aa3b, v2
	v_exp_f32_e32 v9, v9
	v_and_b32_e32 v3, 0xffff0000, v225
	v_add_f32_e32 v9, 1.0, v9
	v_rcp_f32_e32 v222, v9
	v_mul_f32_e32 v9, 0xbfb8aa3b, v3
	v_exp_f32_e32 v9, v9
	s_nop 0
	v_add_f32_e32 v9, 1.0, v9
	v_rcp_f32_e32 v223, v9
	s_nop 0
	v_pk_mul_f32 v[2:3], v[222:223], v[2:3]
	s_nop 0
	v_pk_mul_f32 v[2:3], v[4:5], v[2:3]
	s_nop 0
	v_cvt_pk_bf16_f32 v9, v2, v3
	global_store_dwordx4 v[140:141], v[6:9], off
	ds_read_b128 v[6:9], v0 offset:47488
	ds_read_b128 v[2:5], v0 offset:47504
	s_waitcnt vmcnt(3)
	v_lshlrev_b32_e32 v14, 16, v226
	v_mul_f32_e32 v0, 0xbfb8aa3b, v14
	v_exp_f32_e32 v0, v0
	v_and_b32_e32 v15, 0xffff0000, v226
	v_lshlrev_b32_e32 v226, 16, v227
	v_and_b32_e32 v227, 0xffff0000, v227
	v_add_f32_e32 v0, 1.0, v0
	v_rcp_f32_e32 v16, v0
	v_mul_f32_e32 v0, 0xbfb8aa3b, v15
	v_exp_f32_e32 v0, v0
	s_nop 0
	v_add_f32_e32 v0, 1.0, v0
	v_rcp_f32_e32 v17, v0
	v_mul_f32_e32 v0, 0xbfb8aa3b, v226
	v_exp_f32_e32 v0, v0
	v_pk_mul_f32 v[14:15], v[16:17], v[14:15]
	s_waitcnt lgkmcnt(1)
	v_pk_mul_f32 v[6:7], v[6:7], v[14:15]
	v_add_f32_e32 v0, 1.0, v0
	v_rcp_f32_e32 v14, v0
	v_mul_f32_e32 v0, 0xbfb8aa3b, v227
	v_exp_f32_e32 v0, v0
	v_cvt_pk_bf16_f32 v6, v6, v7
	v_add_f32_e32 v0, 1.0, v0
	v_rcp_f32_e32 v15, v0
	s_nop 0
	v_pk_mul_f32 v[226:227], v[14:15], v[226:227]
	s_nop 0
	v_pk_mul_f32 v[8:9], v[8:9], v[226:227]
	s_nop 0
	v_cvt_pk_bf16_f32 v7, v8, v9
	v_lshlrev_b32_e32 v8, 16, v228
	v_mul_f32_e32 v0, 0xbfb8aa3b, v8
	v_exp_f32_e32 v0, v0
	v_and_b32_e32 v9, 0xffff0000, v228
	v_add_f32_e32 v0, 1.0, v0
	v_rcp_f32_e32 v226, v0
	v_mul_f32_e32 v0, 0xbfb8aa3b, v9
	v_exp_f32_e32 v0, v0
	s_nop 0
	v_add_f32_e32 v0, 1.0, v0
	v_rcp_f32_e32 v227, v0
	s_nop 0
	v_pk_mul_f32 v[8:9], v[226:227], v[8:9]
	s_waitcnt lgkmcnt(0)
	v_pk_mul_f32 v[2:3], v[2:3], v[8:9]
	s_nop 0
	v_cvt_pk_bf16_f32 v8, v2, v3
	v_lshlrev_b32_e32 v2, 16, v229
	v_mul_f32_e32 v0, 0xbfb8aa3b, v2
	v_exp_f32_e32 v0, v0
	v_and_b32_e32 v3, 0xffff0000, v229
	v_add_f32_e32 v0, 1.0, v0
	v_rcp_f32_e32 v226, v0
	v_mul_f32_e32 v0, 0xbfb8aa3b, v3
	v_exp_f32_e32 v0, v0
	s_nop 0
	v_add_f32_e32 v0, 1.0, v0
	v_rcp_f32_e32 v227, v0
	s_nop 0
	v_pk_mul_f32 v[2:3], v[226:227], v[2:3]
	s_nop 0
	v_pk_mul_f32 v[2:3], v[4:5], v[2:3]
	s_nop 0
	v_cvt_pk_bf16_f32 v9, v2, v3
	global_store_dwordx4 v[136:137], v[6:9], off

; #define LAS __attribute__((address_space(3)))
; __device__ __forceinline__ unsigned pk2(float lo, float hi) { f32x2_t v = {lo, hi}; bf16x2_t b = __builtin_convertvector(v, bf16x2_t); return __builtin_bit_cast(unsigned, b); }
; __device__ __forceinline__ float silu_f(float v) { return v * __builtin_amdgcn_rcpf(1.0f + __expf(-v)); }
; template <bool TRACK> ...
;     ...
;     const float ltot = TRACK ? lsum + __shfl_xor(lsum, 32) : lacc[0]; const float inv = 1.0f / ltot;
;     {
;         LAS unsigned char* scr = lds + 40960 + wave * 8704;
; #pragma unroll
;         for (int dh = 0; dh < 2; ++dh)
; #pragma unroll
;             for (int rg = 0; rg < 4; ++rg) { const int d = dh * 32 + 8 * rg + 4 * hi;
;                 f32x4 ov; ov.x = (dh == 0 ? o0[4 * rg] : o1[4 * rg]) * inv; ov.y = (dh == 0 ? o0[4 * rg + 1] : o1[4 * rg + 1]) * inv; ov.z = (dh == 0 ? o0[4 * rg + 2] : o1[4 * rg + 2]) * inv; ov.w = (dh == 0 ? o0[4 * rg + 3] : o1[4 * rg + 3]) * inv;
;                 *(LAS f32x4*)(scr + r32 * 272 + d * 4) = ov; }
;         const int pc = lane & 7;
; #pragma unroll
;         for (int i = 0; i < 4; ++i) { const int rw = i * 8 + (lane >> 3), row = wave * 32 + rw;
;             const f32x4 oa = *(const LAS f32x4*)(scr + rw * 272 + pc * 32), ob = *(const LAS f32x4*)(scr + rw * 272 + pc * 32 + 16);
;             float gv[8]; unpack8(*(const u32x4*)(gate + (size_t)row * INW + 8 * pc), gv);
;             u32x4 w; w.x = pk2(oa.x * silu_f(gv[0]), oa.y * silu_f(gv[1])); w.y = pk2(oa.z * silu_f(gv[2]), oa.w * silu_f(gv[3]));
;             w.z = pk2(ob.x * silu_f(gv[4]), ob.y * silu_f(gv[5])); w.w = pk2(ob.z * silu_f(gv[6]), ob.w * silu_f(gv[7]));
;             *(u32x4*)(outp + (size_t)row * DM + 8 * pc) = w; }
.LBB0_204:
	global_load_dwordx4 v[214:217], v[140:141], off
	global_load_dwordx4 v[218:221], v[136:137], off
	global_load_dwordx4 v[222:225], v[132:133], off
	global_load_dwordx4 v[226:229], v[128:129], off
	s_nop 4
	v_div_scale_f32 v0, s[20:21], v2, v2, 1.0
	v_rcp_f32_e32 v3, v0
	s_nop 0
	v_fma_f32 v4, -v0, v3, 1.0
	v_fmac_f32_e32 v3, v4, v3
	v_div_scale_f32 v4, vcc, 1.0, v2, 1.0
	v_mul_f32_e32 v5, v4, v3
	v_fma_f32 v6, -v0, v5, v4
	v_fmac_f32_e32 v5, v6, v3
	v_fma_f32 v0, -v0, v5, v4
	v_div_fmas_f32 v0, v0, v3, v5
	v_div_fixup_f32 v0, v0, v2, 1.0
	v_pk_mul_f32 v[2:3], v[0:1], v[18:19] op_sel_hi:[0,1]
	v_pk_mul_f32 v[4:5], v[0:1], v[20:21] op_sel_hi:[0,1]
	v_add_u32_e32 v6, v155, v144
	ds_write_b128 v6, v[2:5] offset:40960
	v_pk_mul_f32 v[2:3], v[0:1], v[22:23] op_sel_hi:[0,1]
	v_pk_mul_f32 v[4:5], v[0:1], v[24:25] op_sel_hi:[0,1]
	ds_write_b128 v6, v[2:5] offset:40992
	v_pk_mul_f32 v[2:3], v[0:1], v[26:27] op_sel_hi:[0,1]
	v_pk_mul_f32 v[4:5], v[0:1], v[28:29] op_sel_hi:[0,1]
	ds_write_b128 v6, v[2:5] offset:41024
	v_pk_mul_f32 v[2:3], v[0:1], v[30:31] op_sel_hi:[0,1]
	v_pk_mul_f32 v[4:5], v[0:1], v[32:33] op_sel_hi:[0,1]
	ds_write_b128 v6, v[2:5] offset:41056
	v_pk_mul_f32 v[2:3], v[0:1], v[34:35] op_sel_hi:[0,1]
	v_pk_mul_f32 v[4:5], v[0:1], v[36:37] op_sel_hi:[0,1]
	ds_write_b128 v6, v[2:5] offset:41088
	v_pk_mul_f32 v[2:3], v[0:1], v[38:39] op_sel_hi:[0,1]
	v_pk_mul_f32 v[4:5], v[0:1], v[40:41] op_sel_hi:[0,1]
	ds_write_b128 v6, v[2:5] offset:41120
	v_pk_mul_f32 v[2:3], v[0:1], v[42:43] op_sel_hi:[0,1]
	v_pk_mul_f32 v[4:5], v[0:1], v[44:45] op_sel_hi:[0,1]
	ds_write_b128 v6, v[2:5] offset:41152
	v_pk_mul_f32 v[2:3], v[0:1], v[46:47] op_sel_hi:[0,1]
	v_pk_mul_f32 v[4:5], v[0:1], v[48:49] op_sel_hi:[0,1]
	ds_write_b128 v6, v[2:5] offset:41184
	v_add_u32_e32 v0, v192, v193
	ds_read_b128 v[6:9], v0 offset:40960
	ds_read_b128 v[2:5], v0 offset:40976
	s_waitcnt vmcnt(3)
	v_lshlrev_b32_e32 v14, 16, v214
	v_and_b32_e32 v15, 0xffff0000, v214
	v_mul_f32_e32 v214, 0xbfb8aa3b, v14
	v_exp_f32_e32 v214, v214
	s_nop 0
	v_add_f32_e32 v214, 1.0, v214
	v_rcp_f32_e32 v16, v214
	v_mul_f32_e32 v214, 0xbfb8aa3b, v15
	v_exp_f32_e32 v214, v214
	s_nop 0
	v_add_f32_e32 v214, 1.0, v214
	v_rcp_f32_e32 v17, v214
	v_lshlrev_b32_e32 v214, 16, v215
	v_and_b32_e32 v215, 0xffff0000, v215
	v_pk_mul_f32 v[14:15], v[16:17], v[14:15]
	s_waitcnt lgkmcnt(1)
	v_pk_mul_f32 v[6:7], v[6:7], v[14:15]
	s_nop 0
	v_cvt_pk_bf16_f32 v6, v6, v7
	v_mul_f32_e32 v7, 0xbfb8aa3b, v214
	v_exp_f32_e32 v7, v7
	s_nop 0
	v_add_f32_e32 v7, 1.0, v7
	v_rcp_f32_e32 v14, v7
	v_mul_f32_e32 v7, 0xbfb8aa3b, v215
	v_exp_f32_e32 v7, v7
	s_nop 0
	v_add_f32_e32 v7, 1.0, v7
	v_rcp_f32_e32 v15, v7
	s_nop 0
	v_pk_mul_f32 v[214:215], v[14:15], v[214:215]
	s_nop 0
	v_pk_mul_f32 v[8:9], v[8:9], v[214:215]
	s_nop 0
	v_cvt_pk_bf16_f32 v7, v8, v9
	v_lshlrev_b32_e32 v8, 16, v216
	v_and_b32_e32 v9, 0xffff0000, v216
	v_mul_f32_e32 v214, 0xbfb8aa3b, v8
	v_mul_f32_e32 v215, 0xbfb8aa3b, v9
	v_exp_f32_e32 v214, v214
	v_exp_f32_e32 v215, v215
	v_add_f32_e32 v214, 1.0, v214
	v_add_f32_e32 v215, 1.0, v215
	v_rcp_f32_e32 v214, v214
	v_rcp_f32_e32 v215, v215
	s_nop 0
	v_pk_mul_f32 v[8:9], v[214:215], v[8:9]
	s_waitcnt lgkmcnt(0)
	v_pk_mul_f32 v[2:3], v[2:3], v[8:9]
	s_nop 0
	v_cvt_pk_bf16_f32 v8, v2, v3
	v_lshlrev_b32_e32 v2, 16, v217
	v_mul_f32_e32 v9, 0xbfb8aa3b, v2
	v_exp_f32_e32 v9, v9
	v_and_b32_e32 v3, 0xffff0000, v217
	v_add_f32_e32 v9, 1.0, v9
	v_rcp_f32_e32 v214, v9
	v_mul_f32_e32 v9, 0xbfb8aa3b, v3
	v_exp_f32_e32 v9, v9
	s_nop 0
	v_add_f32_e32 v9, 1.0, v9
	v_rcp_f32_e32 v215, v9
	s_nop 0
	v_pk_mul_f32 v[2:3], v[214:215], v[2:3]
	s_nop 0
	v_pk_mul_f32 v[2:3], v[4:5], v[2:3]
	s_nop 0
	v_cvt_pk_bf16_f32 v9, v2, v3
	global_store_dwordx4 v[138:139], v[6:9], off offset:1280
	ds_read_b128 v[6:9], v0 offset:43136
	ds_read_b128 v[2:5], v0 offset:43152
	s_waitcnt vmcnt(3)
	v_lshlrev_b32_e32 v14, 16, v218
	v_and_b32_e32 v15, 0xffff0000, v218
	v_mul_f32_e32 v218, 0xbfb8aa3b, v14
	v_exp_f32_e32 v218, v218
	s_nop 0
	v_add_f32_e32 v218, 1.0, v218
	v_rcp_f32_e32 v16, v218
	v_mul_f32_e32 v218, 0xbfb8aa3b, v15
	v_exp_f32_e32 v218, v218
	s_nop 0
	v_add_f32_e32 v218, 1.0, v218
	v_rcp_f32_e32 v17, v218
	v_lshlrev_b32_e32 v218, 16, v219
	v_and_b32_e32 v219, 0xffff0000, v219
	v_pk_mul_f32 v[14:15], v[16:17], v[14:15]
	s_waitcnt lgkmcnt(1)
	v_pk_mul_f32 v[6:7], v[6:7], v[14:15]
	s_nop 0
	v_cvt_pk_bf16_f32 v6, v6, v7
	v_mul_f32_e32 v7, 0xbfb8aa3b, v218
	v_exp_f32_e32 v7, v7
	s_nop 0
	v_add_f32_e32 v7, 1.0, v7
	v_rcp_f32_e32 v14, v7
	v_mul_f32_e32 v7, 0xbfb8aa3b, v219
	v_exp_f32_e32 v7, v7
	s_nop 0
	v_add_f32_e32 v7, 1.0, v7
	v_rcp_f32_e32 v15, v7
	s_nop 0
	v_pk_mul_f32 v[218:219], v[14:15], v[218:219]
	s_nop 0
	v_pk_mul_f32 v[8:9], v[8:9], v[218:219]
	s_nop 0
	v_cvt_pk_bf16_f32 v7, v8, v9
	v_lshlrev_b32_e32 v8, 16, v220
	v_and_b32_e32 v9, 0xffff0000, v220
	v_mul_f32_e32 v218, 0xbfb8aa3b, v8
	v_mul_f32_e32 v219, 0xbfb8aa3b, v9
	v_exp_f32_e32 v218, v218
	v_exp_f32_e32 v219, v219
	v_add_f32_e32 v218, 1.0, v218
	v_add_f32_e32 v219, 1.0, v219
	v_rcp_f32_e32 v218, v218
	v_rcp_f32_e32 v219, v219
	s_nop 0
	v_pk_mul_f32 v[8:9], v[218:219], v[8:9]
	s_waitcnt lgkmcnt(0)
; #define LAS __attribute__((address_space(3)))
; __device__ __forceinline__ unsigned pk2(float lo, float hi) { f32x2_t v = {lo, hi}; bf16x2_t b = __builtin_convertvector(v, bf16x2_t); return __builtin_bit_cast(unsigned, b); }
; __device__ __forceinline__ float silu_f(float v) { return v * __builtin_amdgcn_rcpf(1.0f + __expf(-v)); }
; template <bool TRACK> ...
;     ...
;         const int pc = lane & 7;
; #pragma unroll
;         for (int i = 0; i < 4; ++i) { const int rw = i * 8 + (lane >> 3), row = wave * 32 + rw;
;             const f32x4 oa = *(const LAS f32x4*)(scr + rw * 272 + pc * 32), ob = *(const LAS f32x4*)(scr + rw * 272 + pc * 32 + 16);
;             float gv[8]; unpack8(*(const u32x4*)(gate + (size_t)row * INW + 8 * pc), gv);
;             u32x4 w; w.x = pk2(oa.x * silu_f(gv[0]), oa.y * silu_f(gv[1])); w.y = pk2(oa.z * silu_f(gv[2]), oa.w * silu_f(gv[3]));
;             w.z = pk2(ob.x * silu_f(gv[4]), ob.y * silu_f(gv[5])); w.w = pk2(ob.z * silu_f(gv[6]), ob.w * silu_f(gv[7]));
;             *(u32x4*)(outp + (size_t)row * DM + 8 * pc) = w; }
	v_pk_mul_f32 v[2:3], v[2:3], v[8:9]
	s_nop 0
	v_cvt_pk_bf16_f32 v8, v2, v3
	v_lshlrev_b32_e32 v2, 16, v221
	v_mul_f32_e32 v9, 0xbfb8aa3b, v2
	v_exp_f32_e32 v9, v9
	v_and_b32_e32 v3, 0xffff0000, v221
	v_add_f32_e32 v9, 1.0, v9
	v_rcp_f32_e32 v218, v9
	v_mul_f32_e32 v9, 0xbfb8aa3b, v3
	v_exp_f32_e32 v9, v9
	s_nop 0
	v_add_f32_e32 v9, 1.0, v9
	v_rcp_f32_e32 v219, v9
	s_nop 0
	v_pk_mul_f32 v[2:3], v[218:219], v[2:3]
	s_nop 0
	v_pk_mul_f32 v[2:3], v[4:5], v[2:3]
	s_nop 0
	v_cvt_pk_bf16_f32 v9, v2, v3
	global_store_dwordx4 v[134:135], v[6:9], off offset:1280
	ds_read_b128 v[6:9], v0 offset:45312
	ds_read_b128 v[2:5], v0 offset:45328
	s_waitcnt vmcnt(3)
	v_lshlrev_b32_e32 v14, 16, v222
	v_and_b32_e32 v15, 0xffff0000, v222
	v_mul_f32_e32 v222, 0xbfb8aa3b, v14
	v_exp_f32_e32 v222, v222
	s_nop 0
	v_add_f32_e32 v222, 1.0, v222
	v_rcp_f32_e32 v16, v222
	v_mul_f32_e32 v222, 0xbfb8aa3b, v15
	v_exp_f32_e32 v222, v222
	s_nop 0
	v_add_f32_e32 v222, 1.0, v222
	v_rcp_f32_e32 v17, v222
	v_lshlrev_b32_e32 v222, 16, v223
	v_and_b32_e32 v223, 0xffff0000, v223
	v_pk_mul_f32 v[14:15], v[16:17], v[14:15]
	s_waitcnt lgkmcnt(1)
	v_pk_mul_f32 v[6:7], v[6:7], v[14:15]
	s_nop 0
	v_cvt_pk_bf16_f32 v6, v6, v7
	v_mul_f32_e32 v7, 0xbfb8aa3b, v222
	v_exp_f32_e32 v7, v7
	s_nop 0
	v_add_f32_e32 v7, 1.0, v7
	v_rcp_f32_e32 v14, v7
	v_mul_f32_e32 v7, 0xbfb8aa3b, v223
	v_exp_f32_e32 v7, v7
	s_nop 0
	v_add_f32_e32 v7, 1.0, v7
	v_rcp_f32_e32 v15, v7
	s_nop 0
	v_pk_mul_f32 v[222:223], v[14:15], v[222:223]
	s_nop 0
	v_pk_mul_f32 v[8:9], v[8:9], v[222:223]
	s_nop 0
	v_cvt_pk_bf16_f32 v7, v8, v9
	v_lshlrev_b32_e32 v8, 16, v224
	v_and_b32_e32 v9, 0xffff0000, v224
	v_mul_f32_e32 v222, 0xbfb8aa3b, v8
	v_mul_f32_e32 v223, 0xbfb8aa3b, v9
	v_exp_f32_e32 v222, v222
	v_exp_f32_e32 v223, v223
	v_add_f32_e32 v222, 1.0, v222
	v_add_f32_e32 v223, 1.0, v223
	v_rcp_f32_e32 v222, v222
	v_rcp_f32_e32 v223, v223
	s_nop 0
	v_pk_mul_f32 v[8:9], v[222:223], v[8:9]
	s_waitcnt lgkmcnt(0)
	v_pk_mul_f32 v[2:3], v[2:3], v[8:9]
	s_nop 0
	v_cvt_pk_bf16_f32 v8, v2, v3
	v_lshlrev_b32_e32 v2, 16, v225
	v_mul_f32_e32 v9, 0xbfb8aa3b, v2
	v_exp_f32_e32 v9, v9
	v_and_b32_e32 v3, 0xffff0000, v225
	v_add_f32_e32 v9, 1.0, v9
	v_rcp_f32_e32 v222, v9
	v_mul_f32_e32 v9, 0xbfb8aa3b, v3
	v_exp_f32_e32 v9, v9
	s_nop 0
	v_add_f32_e32 v9, 1.0, v9
	v_rcp_f32_e32 v223, v9
	s_nop 0
	v_pk_mul_f32 v[2:3], v[222:223], v[2:3]
	s_nop 0
	v_pk_mul_f32 v[2:3], v[4:5], v[2:3]
	s_nop 0
	v_cvt_pk_bf16_f32 v9, v2, v3
	global_store_dwordx4 v[130:131], v[6:9], off offset:1280
	ds_read_b128 v[6:9], v0 offset:47488
	ds_read_b128 v[2:5], v0 offset:47504
	s_waitcnt vmcnt(3)
	v_lshlrev_b32_e32 v14, 16, v226
	v_mul_f32_e32 v0, 0xbfb8aa3b, v14
	v_exp_f32_e32 v0, v0
	v_and_b32_e32 v15, 0xffff0000, v226
	v_lshlrev_b32_e32 v226, 16, v227
	v_and_b32_e32 v227, 0xffff0000, v227
	v_add_f32_e32 v0, 1.0, v0
	v_rcp_f32_e32 v16, v0
	v_mul_f32_e32 v0, 0xbfb8aa3b, v15
	v_exp_f32_e32 v0, v0
	s_nop 0
	v_add_f32_e32 v0, 1.0, v0
	v_rcp_f32_e32 v17, v0
	v_mul_f32_e32 v0, 0xbfb8aa3b, v226
	v_exp_f32_e32 v0, v0
	v_pk_mul_f32 v[14:15], v[16:17], v[14:15]
	s_waitcnt lgkmcnt(1)
	v_pk_mul_f32 v[6:7], v[6:7], v[14:15]
	v_add_f32_e32 v0, 1.0, v0
	v_rcp_f32_e32 v14, v0
	v_mul_f32_e32 v0, 0xbfb8aa3b, v227
	v_exp_f32_e32 v0, v0
	v_cvt_pk_bf16_f32 v6, v6, v7
	v_add_f32_e32 v0, 1.0, v0
	v_rcp_f32_e32 v15, v0
	s_nop 0
	v_pk_mul_f32 v[226:227], v[14:15], v[226:227]
	s_nop 0
	v_pk_mul_f32 v[8:9], v[8:9], v[226:227]
	s_nop 0
	v_cvt_pk_bf16_f32 v7, v8, v9
	v_lshlrev_b32_e32 v8, 16, v228
	v_mul_f32_e32 v0, 0xbfb8aa3b, v8
	v_exp_f32_e32 v0, v0
	v_and_b32_e32 v9, 0xffff0000, v228
	v_add_f32_e32 v0, 1.0, v0
	v_rcp_f32_e32 v226, v0
	v_mul_f32_e32 v0, 0xbfb8aa3b, v9
	v_exp_f32_e32 v0, v0
	s_nop 0
	v_add_f32_e32 v0, 1.0, v0
	v_rcp_f32_e32 v227, v0
	s_nop 0
	v_pk_mul_f32 v[8:9], v[226:227], v[8:9]
	s_waitcnt lgkmcnt(0)
	v_pk_mul_f32 v[2:3], v[2:3], v[8:9]
	s_nop 0
	v_cvt_pk_bf16_f32 v8, v2, v3
	v_lshlrev_b32_e32 v2, 16, v229
	v_mul_f32_e32 v0, 0xbfb8aa3b, v2
	v_exp_f32_e32 v0, v0
	v_and_b32_e32 v3, 0xffff0000, v229
	v_add_f32_e32 v0, 1.0, v0
	v_rcp_f32_e32 v226, v0
	v_mul_f32_e32 v0, 0xbfb8aa3b, v3
	v_exp_f32_e32 v0, v0
	s_nop 0
	v_add_f32_e32 v0, 1.0, v0
	v_rcp_f32_e32 v227, v0
	s_nop 0
	v_pk_mul_f32 v[2:3], v[226:227], v[2:3]
	s_nop 0
	v_pk_mul_f32 v[2:3], v[4:5], v[2:3]
	s_nop 0
	v_cvt_pk_bf16_f32 v9, v2, v3
	global_store_dwordx4 v[126:127], v[6:9], off offset:1280
